# speedup vs baseline: 1.1364x; 1.0110x over previous
.LBB0_776:
	s_andn2_b64 vcc, exec, s[4:5]
	s_cbranch_vccnz .LBB0_888
	v_readlane_b32 s0, v233, 23
	s_cmp_eq_u32 s0, 1
	s_mov_b64 s[4:5], -1
	s_cbranch_scc1 .LBB0_849
	v_readlane_b32 s0, v235, 60
	v_readlane_b32 s1, v235, 61
	s_andn2_b64 vcc, exec, s[0:1]
	s_cbranch_vccnz .LBB0_848
	v_readlane_b32 s0, v236, 0
	s_cmpk_lg_u32 s0, 0x200
	s_cbranch_scc1 .Lada_orig
	s_branch .Lada_entry
.Lada_orig:
	s_mov_b32 s28, s2
	s_branch .LBB0_782

.Lada_entry:
	s_cmpk_lt_u32 s2, 0xc0
	s_cbranch_scc0 .Lada_skip
	v_and_b32_e32 v94, 31, v93
	v_bfe_u32 v95, v93, 5, 1
	v_lshrrev_b32_e32 v96, 6, v93
	s_nop 0
	v_readfirstlane_b32 s14, v96
	s_lshl_b32 s15, s2, 5
	v_add_u32_e32 v96, s15, v94
	v_lshlrev_b32_e32 v96, 2, v96
	v_mul_u32_u24_e32 v82, 0xc0000, v95
	v_add_u32_e32 v82, v82, v96
	v_readlane_b32 s4, v233, 7
	v_readlane_b32 s5, v233, 8
	v_readlane_b32 s6, v233, 15
	v_readlane_b32 s7, v233, 16
	v_cmp_gt_u32_e64 s[10:11], 8, v94
	v_cmp_eq_u32_e64 s[12:13], 8, v94
	v_cmp_gt_u32_e64 s[16:17], 9, v94
	v_lshlrev_b32_e32 v80, 13, v94
	v_mov_b32_e32 v81, 0
	s_nop 1
	v_cndmask_b32_e64 v80, 0, v80, s[10:11]
	v_lshl_add_u64 v[80:81], v[80:81], 0, s[4:5]
	v_mov_b32_e32 v96, s6
	v_mov_b32_e32 v97, s7
	v_cndmask_b32_e64 v80, v80, v96, s[12:13]
	v_cndmask_b32_e64 v81, v81, v97, s[12:13]
	s_lshl_b32 s0, s14, 11
	v_lshl_add_u32 v96, v95, 7, s0
	v_mov_b32_e32 v97, 0
	v_lshl_add_u64 v[80:81], v[80:81], 0, v[96:97]
	v_readlane_b32 s8, v233, 17
	v_readlane_b32 s9, v233, 18
	s_mul_i32 s0, s14, 0xc00000
	s_add_u32 s8, s8, s0
	s_addc_u32 s9, s9, 0
	v_mov_b32_e32 v64, 0
	v_mov_b32_e32 v65, 0
	v_mov_b32_e32 v66, 0
	v_mov_b32_e32 v67, 0
	v_mov_b32_e32 v68, 0
	v_mov_b32_e32 v69, 0
	v_mov_b32_e32 v70, 0
	v_mov_b32_e32 v71, 0
	v_mov_b32_e32 v72, 0
	v_mov_b32_e32 v73, 0
	v_mov_b32_e32 v74, 0
	v_mov_b32_e32 v75, 0
	v_mov_b32_e32 v76, 0
	v_mov_b32_e32 v77, 0
	v_mov_b32_e32 v78, 0
	v_mov_b32_e32 v79, 0
	s_movk_i32 s18, 8
.Lada_sc:
	global_load_dword v0, v[80:81], off offset:0
	global_load_dword v1, v[80:81], off offset:4
	global_load_dword v2, v[80:81], off offset:8
	global_load_dword v3, v[80:81], off offset:12
	global_load_dword v4, v[80:81], off offset:16
	global_load_dword v5, v[80:81], off offset:20
	global_load_dword v6, v[80:81], off offset:24
	global_load_dword v7, v[80:81], off offset:28
	global_load_dword v8, v[80:81], off offset:32
	global_load_dword v9, v[80:81], off offset:36
	global_load_dword v10, v[80:81], off offset:40
	global_load_dword v11, v[80:81], off offset:44
	global_load_dword v12, v[80:81], off offset:48
	global_load_dword v13, v[80:81], off offset:52
	global_load_dword v14, v[80:81], off offset:56
	global_load_dword v15, v[80:81], off offset:60
	global_load_dword v16, v[80:81], off offset:64
	global_load_dword v17, v[80:81], off offset:68
	global_load_dword v18, v[80:81], off offset:72
	global_load_dword v19, v[80:81], off offset:76
	global_load_dword v20, v[80:81], off offset:80
	global_load_dword v21, v[80:81], off offset:84
	global_load_dword v22, v[80:81], off offset:88
	global_load_dword v23, v[80:81], off offset:92
	global_load_dword v24, v[80:81], off offset:96
	global_load_dword v25, v[80:81], off offset:100
	global_load_dword v26, v[80:81], off offset:104
	global_load_dword v27, v[80:81], off offset:108
	global_load_dword v28, v[80:81], off offset:112
	global_load_dword v29, v[80:81], off offset:116
	global_load_dword v30, v[80:81], off offset:120
	global_load_dword v31, v[80:81], off offset:124
	s_add_u32 s0, s8, 0x0
	s_addc_u32 s1, s9, 0
	global_load_dword v32, v82, s[0:1]
	s_add_u32 s0, s8, 0x6000
	s_addc_u32 s1, s9, 0
	global_load_dword v33, v82, s[0:1]
	s_add_u32 s0, s8, 0xc000
	s_addc_u32 s1, s9, 0
	global_load_dword v34, v82, s[0:1]
	s_add_u32 s0, s8, 0x12000
	s_addc_u32 s1, s9, 0
	global_load_dword v35, v82, s[0:1]
	s_add_u32 s0, s8, 0x18000
	s_addc_u32 s1, s9, 0
	global_load_dword v36, v82, s[0:1]
	s_add_u32 s0, s8, 0x1e000
	s_addc_u32 s1, s9, 0
	global_load_dword v37, v82, s[0:1]
	s_add_u32 s0, s8, 0x24000
	s_addc_u32 s1, s9, 0
	global_load_dword v38, v82, s[0:1]
	s_add_u32 s0, s8, 0x2a000
	s_addc_u32 s1, s9, 0
	global_load_dword v39, v82, s[0:1]
	s_add_u32 s0, s8, 0x30000
	s_addc_u32 s1, s9, 0
	global_load_dword v40, v82, s[0:1]
	s_add_u32 s0, s8, 0x36000
	s_addc_u32 s1, s9, 0
	global_load_dword v41, v82, s[0:1]
	s_add_u32 s0, s8, 0x3c000
	s_addc_u32 s1, s9, 0
	global_load_dword v42, v82, s[0:1]
	s_add_u32 s0, s8, 0x42000
	s_addc_u32 s1, s9, 0
	global_load_dword v43, v82, s[0:1]
	s_add_u32 s0, s8, 0x48000
	s_addc_u32 s1, s9, 0
	global_load_dword v44, v82, s[0:1]
	s_add_u32 s0, s8, 0x4e000
	s_addc_u32 s1, s9, 0
	global_load_dword v45, v82, s[0:1]
	s_add_u32 s0, s8, 0x54000
	s_addc_u32 s1, s9, 0
	global_load_dword v46, v82, s[0:1]
	s_add_u32 s0, s8, 0x5a000
	s_addc_u32 s1, s9, 0
	global_load_dword v47, v82, s[0:1]
	s_add_u32 s0, s8, 0x60000
	s_addc_u32 s1, s9, 0
	global_load_dword v48, v82, s[0:1]
	s_add_u32 s0, s8, 0x66000
	s_addc_u32 s1, s9, 0
	global_load_dword v49, v82, s[0:1]
	s_add_u32 s0, s8, 0x6c000
	s_addc_u32 s1, s9, 0
	global_load_dword v50, v82, s[0:1]
	s_add_u32 s0, s8, 0x72000
	s_addc_u32 s1, s9, 0
	global_load_dword v51, v82, s[0:1]
	s_add_u32 s0, s8, 0x78000
	s_addc_u32 s1, s9, 0
	global_load_dword v52, v82, s[0:1]
	s_add_u32 s0, s8, 0x7e000
	s_addc_u32 s1, s9, 0
	global_load_dword v53, v82, s[0:1]
	s_add_u32 s0, s8, 0x84000
	s_addc_u32 s1, s9, 0
	global_load_dword v54, v82, s[0:1]
	s_add_u32 s0, s8, 0x8a000
	s_addc_u32 s1, s9, 0
	global_load_dword v55, v82, s[0:1]
	s_add_u32 s0, s8, 0x90000
	s_addc_u32 s1, s9, 0
	global_load_dword v56, v82, s[0:1]
	s_add_u32 s0, s8, 0x96000
	s_addc_u32 s1, s9, 0
	global_load_dword v57, v82, s[0:1]
	s_add_u32 s0, s8, 0x9c000
	s_addc_u32 s1, s9, 0
	global_load_dword v58, v82, s[0:1]
	s_add_u32 s0, s8, 0xa2000
	s_addc_u32 s1, s9, 0
	global_load_dword v59, v82, s[0:1]
	s_add_u32 s0, s8, 0xa8000
	s_addc_u32 s1, s9, 0
	global_load_dword v60, v82, s[0:1]
	s_add_u32 s0, s8, 0xae000
	s_addc_u32 s1, s9, 0
	global_load_dword v61, v82, s[0:1]
	s_add_u32 s0, s8, 0xb4000
	s_addc_u32 s1, s9, 0
	global_load_dword v62, v82, s[0:1]
	s_add_u32 s0, s8, 0xba000
	s_addc_u32 s1, s9, 0
	global_load_dword v63, v82, s[0:1]
	s_waitcnt vmcnt(0)
	v_mul_f32_e32 v100, 0xbfb8aa3b, v0
	v_mul_f32_e32 v101, 0xbfb8aa3b, v1
	v_mul_f32_e32 v102, 0xbfb8aa3b, v2
	v_mul_f32_e32 v103, 0xbfb8aa3b, v3
	v_mul_f32_e32 v104, 0xbfb8aa3b, v4
	v_mul_f32_e32 v105, 0xbfb8aa3b, v5
	v_mul_f32_e32 v106, 0xbfb8aa3b, v6
	v_mul_f32_e32 v107, 0xbfb8aa3b, v7
	v_mul_f32_e32 v108, 0xbfb8aa3b, v8
	v_mul_f32_e32 v109, 0xbfb8aa3b, v9
	v_mul_f32_e32 v110, 0xbfb8aa3b, v10
	v_mul_f32_e32 v111, 0xbfb8aa3b, v11
	v_mul_f32_e32 v112, 0xbfb8aa3b, v12
	v_mul_f32_e32 v113, 0xbfb8aa3b, v13
	v_mul_f32_e32 v114, 0xbfb8aa3b, v14
	v_mul_f32_e32 v115, 0xbfb8aa3b, v15
	v_mul_f32_e32 v116, 0xbfb8aa3b, v16
	v_mul_f32_e32 v117, 0xbfb8aa3b, v17
	v_mul_f32_e32 v118, 0xbfb8aa3b, v18
	v_mul_f32_e32 v119, 0xbfb8aa3b, v19
	v_mul_f32_e32 v120, 0xbfb8aa3b, v20
	v_mul_f32_e32 v121, 0xbfb8aa3b, v21
	v_mul_f32_e32 v122, 0xbfb8aa3b, v22
	v_mul_f32_e32 v123, 0xbfb8aa3b, v23
	v_mul_f32_e32 v124, 0xbfb8aa3b, v24
	v_mul_f32_e32 v125, 0xbfb8aa3b, v25
	v_mul_f32_e32 v126, 0xbfb8aa3b, v26
	v_mul_f32_e32 v127, 0xbfb8aa3b, v27
	v_mul_f32_e32 v128, 0xbfb8aa3b, v28
	v_mul_f32_e32 v129, 0xbfb8aa3b, v29
	v_mul_f32_e32 v130, 0xbfb8aa3b, v30
	v_mul_f32_e32 v131, 0xbfb8aa3b, v31
	v_exp_f32_e32 v100, v100
	v_exp_f32_e32 v101, v101
	v_exp_f32_e32 v102, v102
	v_exp_f32_e32 v103, v103
	v_exp_f32_e32 v104, v104
	v_exp_f32_e32 v105, v105
	v_exp_f32_e32 v106, v106
	v_exp_f32_e32 v107, v107
	v_exp_f32_e32 v108, v108
	v_exp_f32_e32 v109, v109
	v_exp_f32_e32 v110, v110
	v_exp_f32_e32 v111, v111
	v_exp_f32_e32 v112, v112
	v_exp_f32_e32 v113, v113
	v_exp_f32_e32 v114, v114
	v_exp_f32_e32 v115, v115
	v_exp_f32_e32 v116, v116
	v_exp_f32_e32 v117, v117
	v_exp_f32_e32 v118, v118
	v_exp_f32_e32 v119, v119
	v_exp_f32_e32 v120, v120
	v_exp_f32_e32 v121, v121
	v_exp_f32_e32 v122, v122
	v_exp_f32_e32 v123, v123
	v_exp_f32_e32 v124, v124
	v_exp_f32_e32 v125, v125
	v_exp_f32_e32 v126, v126
	v_exp_f32_e32 v127, v127
	v_exp_f32_e32 v128, v128
	v_exp_f32_e32 v129, v129
	v_exp_f32_e32 v130, v130
	v_exp_f32_e32 v131, v131
	v_add_f32_e32 v100, 1.0, v100
	v_add_f32_e32 v101, 1.0, v101
	v_add_f32_e32 v102, 1.0, v102
	v_add_f32_e32 v103, 1.0, v103
	v_add_f32_e32 v104, 1.0, v104
	v_add_f32_e32 v105, 1.0, v105
	v_add_f32_e32 v106, 1.0, v106
	v_add_f32_e32 v107, 1.0, v107
	v_add_f32_e32 v108, 1.0, v108
	v_add_f32_e32 v109, 1.0, v109
	v_add_f32_e32 v110, 1.0, v110
	v_add_f32_e32 v111, 1.0, v111
	v_add_f32_e32 v112, 1.0, v112
	v_add_f32_e32 v113, 1.0, v113
	v_add_f32_e32 v114, 1.0, v114
	v_add_f32_e32 v115, 1.0, v115
	v_add_f32_e32 v116, 1.0, v116
	v_add_f32_e32 v117, 1.0, v117
	v_add_f32_e32 v118, 1.0, v118
	v_add_f32_e32 v119, 1.0, v119
	v_add_f32_e32 v120, 1.0, v120
	v_add_f32_e32 v121, 1.0, v121
	v_add_f32_e32 v122, 1.0, v122
	v_add_f32_e32 v123, 1.0, v123
	v_add_f32_e32 v124, 1.0, v124
	v_add_f32_e32 v125, 1.0, v125
	v_add_f32_e32 v126, 1.0, v126
	v_add_f32_e32 v127, 1.0, v127
	v_add_f32_e32 v128, 1.0, v128
	v_add_f32_e32 v129, 1.0, v129
	v_add_f32_e32 v130, 1.0, v130
	v_add_f32_e32 v131, 1.0, v131
	v_rcp_f32_e32 v100, v100
	v_rcp_f32_e32 v101, v101
	v_rcp_f32_e32 v102, v102
	v_rcp_f32_e32 v103, v103
	v_rcp_f32_e32 v104, v104
	v_rcp_f32_e32 v105, v105
	v_rcp_f32_e32 v106, v106
	v_rcp_f32_e32 v107, v107
	v_rcp_f32_e32 v108, v108
	v_rcp_f32_e32 v109, v109
	v_rcp_f32_e32 v110, v110
	v_rcp_f32_e32 v111, v111
	v_rcp_f32_e32 v112, v112
	v_rcp_f32_e32 v113, v113
	v_rcp_f32_e32 v114, v114
	v_rcp_f32_e32 v115, v115
	v_rcp_f32_e32 v116, v116
	v_rcp_f32_e32 v117, v117
	v_rcp_f32_e32 v118, v118
	v_rcp_f32_e32 v119, v119
	v_rcp_f32_e32 v120, v120
	v_rcp_f32_e32 v121, v121
	v_rcp_f32_e32 v122, v122
	v_rcp_f32_e32 v123, v123
	v_rcp_f32_e32 v124, v124
	v_rcp_f32_e32 v125, v125
	v_rcp_f32_e32 v126, v126
	v_rcp_f32_e32 v127, v127
	v_rcp_f32_e32 v128, v128
	v_rcp_f32_e32 v129, v129
	v_rcp_f32_e32 v130, v130
	v_rcp_f32_e32 v131, v131
	v_mul_f32_e32 v0, v0, v100
	v_mul_f32_e32 v1, v1, v101
	v_mul_f32_e32 v2, v2, v102
	v_mul_f32_e32 v3, v3, v103
	v_mul_f32_e32 v4, v4, v104
	v_mul_f32_e32 v5, v5, v105
	v_mul_f32_e32 v6, v6, v106
	v_mul_f32_e32 v7, v7, v107
	v_mul_f32_e32 v8, v8, v108
	v_mul_f32_e32 v9, v9, v109
	v_mul_f32_e32 v10, v10, v110
	v_mul_f32_e32 v11, v11, v111
	v_mul_f32_e32 v12, v12, v112
	v_mul_f32_e32 v13, v13, v113
	v_mul_f32_e32 v14, v14, v114
	v_mul_f32_e32 v15, v15, v115
	v_mul_f32_e32 v16, v16, v116
	v_mul_f32_e32 v17, v17, v117
	v_mul_f32_e32 v18, v18, v118
	v_mul_f32_e32 v19, v19, v119
	v_mul_f32_e32 v20, v20, v120
	v_mul_f32_e32 v21, v21, v121
	v_mul_f32_e32 v22, v22, v122
	v_mul_f32_e32 v23, v23, v123
	v_mul_f32_e32 v24, v24, v124
	v_mul_f32_e32 v25, v25, v125
	v_mul_f32_e32 v26, v26, v126
	v_mul_f32_e32 v27, v27, v127
	v_mul_f32_e32 v28, v28, v128
	v_mul_f32_e32 v29, v29, v129
	v_mul_f32_e32 v30, v30, v130
	v_mul_f32_e32 v31, v31, v131
	v_cndmask_b32_e64 v0, 0, v0, s[16:17]
	v_cndmask_b32_e64 v1, 0, v1, s[16:17]
	v_cndmask_b32_e64 v2, 0, v2, s[16:17]
	v_cndmask_b32_e64 v3, 0, v3, s[16:17]
	v_cndmask_b32_e64 v4, 0, v4, s[16:17]
	v_cndmask_b32_e64 v5, 0, v5, s[16:17]
	v_cndmask_b32_e64 v6, 0, v6, s[16:17]
	v_cndmask_b32_e64 v7, 0, v7, s[16:17]
	v_cndmask_b32_e64 v8, 0, v8, s[16:17]
	v_cndmask_b32_e64 v9, 0, v9, s[16:17]
	v_cndmask_b32_e64 v10, 0, v10, s[16:17]
	v_cndmask_b32_e64 v11, 0, v11, s[16:17]
	v_cndmask_b32_e64 v12, 0, v12, s[16:17]
	v_cndmask_b32_e64 v13, 0, v13, s[16:17]
	v_cndmask_b32_e64 v14, 0, v14, s[16:17]
	v_cndmask_b32_e64 v15, 0, v15, s[16:17]
	v_cndmask_b32_e64 v16, 0, v16, s[16:17]
	v_cndmask_b32_e64 v17, 0, v17, s[16:17]
	v_cndmask_b32_e64 v18, 0, v18, s[16:17]
	v_cndmask_b32_e64 v19, 0, v19, s[16:17]
	v_cndmask_b32_e64 v20, 0, v20, s[16:17]
	v_cndmask_b32_e64 v21, 0, v21, s[16:17]
	v_cndmask_b32_e64 v22, 0, v22, s[16:17]
	v_cndmask_b32_e64 v23, 0, v23, s[16:17]
	v_cndmask_b32_e64 v24, 0, v24, s[16:17]
	v_cndmask_b32_e64 v25, 0, v25, s[16:17]
	v_cndmask_b32_e64 v26, 0, v26, s[16:17]
	v_cndmask_b32_e64 v27, 0, v27, s[16:17]
	v_cndmask_b32_e64 v28, 0, v28, s[16:17]
	v_cndmask_b32_e64 v29, 0, v29, s[16:17]
	v_cndmask_b32_e64 v30, 0, v30, s[16:17]
	v_cndmask_b32_e64 v31, 0, v31, s[16:17]
	s_nop 1
	v_mfma_f32_32x32x2_f32 v[64:79], v0, v32, v[64:79]
	v_mfma_f32_32x32x2_f32 v[64:79], v1, v33, v[64:79]
	v_mfma_f32_32x32x2_f32 v[64:79], v2, v34, v[64:79]
	v_mfma_f32_32x32x2_f32 v[64:79], v3, v35, v[64:79]
	v_mfma_f32_32x32x2_f32 v[64:79], v4, v36, v[64:79]
	v_mfma_f32_32x32x2_f32 v[64:79], v5, v37, v[64:79]
	v_mfma_f32_32x32x2_f32 v[64:79], v6, v38, v[64:79]
	v_mfma_f32_32x32x2_f32 v[64:79], v7, v39, v[64:79]
	v_mfma_f32_32x32x2_f32 v[64:79], v8, v40, v[64:79]
	v_mfma_f32_32x32x2_f32 v[64:79], v9, v41, v[64:79]
	v_mfma_f32_32x32x2_f32 v[64:79], v10, v42, v[64:79]
	v_mfma_f32_32x32x2_f32 v[64:79], v11, v43, v[64:79]
	v_mfma_f32_32x32x2_f32 v[64:79], v12, v44, v[64:79]
	v_mfma_f32_32x32x2_f32 v[64:79], v13, v45, v[64:79]
	v_mfma_f32_32x32x2_f32 v[64:79], v14, v46, v[64:79]
	v_mfma_f32_32x32x2_f32 v[64:79], v15, v47, v[64:79]
	v_mfma_f32_32x32x2_f32 v[64:79], v16, v48, v[64:79]
	v_mfma_f32_32x32x2_f32 v[64:79], v17, v49, v[64:79]
	v_mfma_f32_32x32x2_f32 v[64:79], v18, v50, v[64:79]
	v_mfma_f32_32x32x2_f32 v[64:79], v19, v51, v[64:79]
	v_mfma_f32_32x32x2_f32 v[64:79], v20, v52, v[64:79]
	v_mfma_f32_32x32x2_f32 v[64:79], v21, v53, v[64:79]
	v_mfma_f32_32x32x2_f32 v[64:79], v22, v54, v[64:79]
	v_mfma_f32_32x32x2_f32 v[64:79], v23, v55, v[64:79]
	v_mfma_f32_32x32x2_f32 v[64:79], v24, v56, v[64:79]
	v_mfma_f32_32x32x2_f32 v[64:79], v25, v57, v[64:79]
	v_mfma_f32_32x32x2_f32 v[64:79], v26, v58, v[64:79]
	v_mfma_f32_32x32x2_f32 v[64:79], v27, v59, v[64:79]
	v_mfma_f32_32x32x2_f32 v[64:79], v28, v60, v[64:79]
	v_mfma_f32_32x32x2_f32 v[64:79], v29, v61, v[64:79]
	v_mfma_f32_32x32x2_f32 v[64:79], v30, v62, v[64:79]
	v_mfma_f32_32x32x2_f32 v[64:79], v31, v63, v[64:79]
	s_add_u32 s8, s8, 0x180000
	s_addc_u32 s9, s9, 0
	v_add_co_u32_e32 v80, vcc, 0x100, v80
	s_nop 1
	v_addc_co_u32_e32 v81, vcc, 0, v81, vcc
	s_add_i32 s18, s18, -1
	s_cmp_lg_u32 s18, 0
	s_cbranch_scc1 .Lada_sc
	s_nop 15
	s_nop 3
	s_lshl_b32 s0, s14, 11
	v_lshlrev_b32_e32 v98, 2, v94
	v_lshl_add_u32 v98, v95, 9, v98
	v_add_u32_e32 v98, s0, v98
	ds_write_b32 v98, v64 offset:0
	ds_write_b32 v98, v65 offset:128
	ds_write_b32 v98, v66 offset:256
	ds_write_b32 v98, v67 offset:384
	ds_write_b32 v98, v68 offset:1024
	s_waitcnt lgkmcnt(0)
	s_barrier
	v_lshrrev_b32_e32 v96, 5, v93
	v_lshlrev_b32_e32 v97, 7, v96
	v_lshl_add_u32 v97, v94, 2, v97
	ds_read_b32 v100, v97 offset:0
	ds_read_b32 v101, v97 offset:2048
	ds_read_b32 v102, v97 offset:4096
	ds_read_b32 v103, v97 offset:6144
	v_readlane_b32 s4, v236, 1
	v_readlane_b32 s5, v236, 2
	v_readlane_b32 s6, v235, 37
	v_readlane_b32 s7, v235, 38
	v_add_u32_e32 v104, s15, v94
	v_lshlrev_b32_e32 v104, 2, v104
	global_load_dword v105, v104, s[4:5]
	v_mul_u32_u24_e32 v106, 0x6000, v96
	v_add_u32_e32 v106, v106, v104
	s_waitcnt vmcnt(0) lgkmcnt(0)
	v_add_f32_e32 v100, v100, v101
	v_add_f32_e32 v102, v102, v103
	v_add_f32_e32 v100, v100, v102
	v_add_f32_e32 v100, v100, v105
	global_store_dword v106, v100, s[6:7]
	s_cmp_lg_u32 s14, 0
	s_cbranch_scc1 .Lada_r8done
	v_lshlrev_b32_e32 v97, 2, v94
	ds_read_b32 v100, v97 offset:1024
	ds_read_b32 v101, v97 offset:3072
	ds_read_b32 v102, v97 offset:5120
	ds_read_b32 v103, v97 offset:7168
	s_waitcnt lgkmcnt(0)
	v_add_f32_e32 v100, v100, v101
	v_add_f32_e32 v102, v102, v103
	v_add_f32_e32 v100, v100, v102
	v_add_f32_e32 v100, v100, v105
	v_add_u32_e32 v106, 0x30000, v104
	s_mov_b64 s[0:1], exec
	s_mov_b64 exec, 0xffffffff
	global_store_dword v106, v100, s[6:7]
	s_mov_b64 exec, s[0:1]
.Lada_r8done:
.Lada_skip:
	s_waitcnt vmcnt(0) lgkmcnt(0)
	s_barrier
	s_add_u32 s0, s2, 0x200
	s_cmpk_lt_u32 s2, 0x60
	s_cselect_b32 s28, s0, s2
	s_branch .LBB0_782
